# diff-attn loop: softmax bias reads hoisted + permlane32_swap max; PV+QK LDS reads software-pipelined 5 MFMAs ahead
# speedup vs baseline: 1.0131x; 1.0131x over previous
; __device__ __forceinline__ void d2_qk(const LAS unsigned char* Kb, const v8s (&Q)[4], v16f& S) {
;     const v16f z = {0.f, 0.f, 0.f, 0.f, 0.f, 0.f, 0.f, 0.f, 0.f, 0.f, 0.f, 0.f, 0.f, 0.f, 0.f, 0.f};
;     const v8s k0 = *(const LAS v8s*)Kb, k1 = *(const LAS v8s*)(Kb + 32), k2 = *(const LAS v8s*)(Kb + 64), k3 = *(const LAS v8s*)(Kb + 96);
;     __builtin_amdgcn_sched_barrier(0);
;     S = MFMA32(k0, Q[0], z); S = MFMA32(k1, Q[1], S); S = MFMA32(k2, Q[2], S); S = MFMA32(k3, Q[3], S);
;     __builtin_amdgcn_sched_barrier(0);
; }
; __device__ __forceinline__ void d2_softmax(v16f& S, const float c1, const LAS float* tp, float& m, float& l, v16f (&O)[4], v8s (&P)[2]) {
;     float tmax = NEGBIG;
; #pragma unroll
;     for (int i = 0; i < 16; ++i) { S[i] = S[i] * c1 + tp[(i & 3) + 8 * (i >> 2)]; tmax = fmaxf(tmax, S[i]); }
;     tmax = fmaxf(tmax, __shfl_xor(tmax, 32));
;     const float mo = m;
;     if (__any(tmax > mo + 8.f)) {
;         const float mn = (tmax > mo + 8.f) ? tmax : mo;
;         const float alpha = __builtin_amdgcn_exp2f(mo - mn);
;         l *= alpha;
; #pragma unroll
;         for (int eb = 0; eb < 4; ++eb)
; #pragma unroll
;             for (int i = 0; i < 16; ++i) O[eb][i] *= alpha;
;         m = mn;
;     }
;     const float mc = m;
;     float ps = 0.f;
; #pragma unroll
;     for (int i = 0; i < 16; ++i) { S[i] = __builtin_amdgcn_exp2f(S[i] - mc); ps += S[i]; }
;     l += ps;
; #pragma unroll
;     for (int s2 = 0; s2 < 2; ++s2) { v4u w; w.x = pk2(S[8 * s2 + 0], S[8 * s2 + 1]); w.y = pk2(S[8 * s2 + 2], S[8 * s2 + 3]); w.z = pk2(S[8 * s2 + 4], S[8 * s2 + 5]); w.w = pk2(S[8 * s2 + 6], S[8 * s2 + 7]);
;         P[s2] = __builtin_bit_cast(v8s, w); }
; }
; __device__ __forceinline__ void d2_pv(const LAS unsigned char* vb0, const v8s (&P)[2], v16f (&O)[4]) {
;     const LAS unsigned char* va = vb0; const LAS unsigned char* vc = vb0 + 16 * 320;
;     const v4s l0 = TRR(va), h0 = TRR(va + 2560), l1 = TRR(va + 64), h1 = TRR(va + 2624), l2 = TRR(va + 128), h2 = TRR(va + 2688), l3 = TRR(va + 192), h3 = TRR(va + 2752);
;     __builtin_amdgcn_sched_barrier(0);
;     const v4s m0 = TRR(vc), n0 = TRR(vc + 2560), m1 = TRR(vc + 64), n1 = TRR(vc + 2624), m2 = TRR(vc + 128), n2 = TRR(vc + 2688), m3 = TRR(vc + 192), n3 = TRR(vc + 2752);
;     O[0] = MFMA32(__builtin_shufflevector(l0, h0, 0, 1, 2, 3, 4, 5, 6, 7), P[0], O[0]);
.LBB0_333:
	s_cmp_eq_u32 s6, 0
	s_cbranch_scc1 .Ld2y1_qkonly
	s_mul_i32 s19, s18, 0x4800
	s_xor_b32 s18, s18, 1
	s_mulk_i32 s18, 0x5000
	v_add_u32_e32 v198, s19, v181
	v_add_u32_e32 v0, s18, v180
	ds_read_b64_tr_b16 v[156:157], v0 offset:36864
	ds_read_b64_tr_b16 v[158:159], v0 offset:39424
	ds_read_b64_tr_b16 v[186:187], v0 offset:36928
	ds_read_b64_tr_b16 v[188:189], v0 offset:39488
	ds_read_b64_tr_b16 v[190:191], v0 offset:36992
	ds_read_b64_tr_b16 v[192:193], v0 offset:39552
	ds_read_b64_tr_b16 v[194:195], v0 offset:37056
	ds_read_b64_tr_b16 v[196:197], v0 offset:39616
	ds_read_b64_tr_b16 v[66:67], v0 offset:41984
	ds_read_b64_tr_b16 v[68:69], v0 offset:44544
	ds_read_b64_tr_b16 v[70:71], v0 offset:42048
	ds_read_b64_tr_b16 v[72:73], v0 offset:44608
	s_waitcnt lgkmcnt(10)
	v_mfma_f32_32x32x16_bf16 v[50:65], v[156:159], v[134:137], v[50:65]
	ds_read_b64_tr_b16 v[74:75], v0 offset:42112
	ds_read_b64_tr_b16 v[76:77], v0 offset:44672
	s_waitcnt lgkmcnt(10)
	v_mfma_f32_32x32x16_bf16 v[34:49], v[186:189], v[134:137], v[34:49]
	ds_read_b64_tr_b16 v[78:79], v0 offset:42176
	ds_read_b64_tr_b16 v[80:81], v0 offset:44736
	s_waitcnt lgkmcnt(10)
	v_mfma_f32_32x32x16_bf16 v[18:33], v[190:193], v[134:137], v[18:33]
	ds_read_b64_tr_b16 v[82:83], v0 offset:47104
	ds_read_b64_tr_b16 v[84:85], v0 offset:49664
	s_waitcnt lgkmcnt(10)
	v_mfma_f32_32x32x16_bf16 v[2:17], v[194:197], v[134:137], v[2:17]
	ds_read_b64_tr_b16 v[86:87], v0 offset:47168
	ds_read_b64_tr_b16 v[88:89], v0 offset:49728
	s_waitcnt lgkmcnt(10)
	v_mfma_f32_32x32x16_bf16 v[50:65], v[66:69], v[130:133], v[50:65]
	ds_read_b64_tr_b16 v[90:91], v0 offset:47232
	ds_read_b64_tr_b16 v[92:93], v0 offset:49792
	s_waitcnt lgkmcnt(10)
	v_mfma_f32_32x32x16_bf16 v[34:49], v[70:73], v[130:133], v[34:49]
	ds_read_b64_tr_b16 v[94:95], v0 offset:47296
	ds_read_b64_tr_b16 v[96:97], v0 offset:49856
	s_waitcnt lgkmcnt(10)
	v_mfma_f32_32x32x16_bf16 v[18:33], v[74:77], v[130:133], v[18:33]
	ds_read_b64_tr_b16 v[156:157], v0 offset:52224
	ds_read_b64_tr_b16 v[158:159], v0 offset:54784
	s_waitcnt lgkmcnt(10)
	v_mfma_f32_32x32x16_bf16 v[2:17], v[78:81], v[130:133], v[2:17]
	ds_read_b64_tr_b16 v[186:187], v0 offset:52288
	ds_read_b64_tr_b16 v[188:189], v0 offset:54848
	s_waitcnt lgkmcnt(10)
	v_mfma_f32_32x32x16_bf16 v[50:65], v[82:85], v[142:145], v[50:65]
	ds_read_b64_tr_b16 v[190:191], v0 offset:52352
	ds_read_b64_tr_b16 v[192:193], v0 offset:54912
	s_waitcnt lgkmcnt(10)
	v_mfma_f32_32x32x16_bf16 v[34:49], v[86:89], v[142:145], v[34:49]
	ds_read_b64_tr_b16 v[194:195], v0 offset:52416
	ds_read_b64_tr_b16 v[196:197], v0 offset:54976
	s_waitcnt lgkmcnt(10)
	v_mfma_f32_32x32x16_bf16 v[18:33], v[90:93], v[142:145], v[18:33]
	ds_read_b128 v[82:85], v198
	s_waitcnt lgkmcnt(9)
	v_mfma_f32_32x32x16_bf16 v[2:17], v[94:97], v[142:145], v[2:17]
	ds_read_b128 v[86:89], v198 offset:32
	s_waitcnt lgkmcnt(8)
	v_mfma_f32_32x32x16_bf16 v[50:65], v[156:159], v[138:141], v[50:65]
	ds_read_b128 v[90:93], v198 offset:64
	s_waitcnt lgkmcnt(7)
	v_mfma_f32_32x32x16_bf16 v[34:49], v[186:189], v[138:141], v[34:49]
	ds_read_b128 v[94:97], v198 offset:96
	s_waitcnt lgkmcnt(6)
	v_mfma_f32_32x32x16_bf16 v[18:33], v[190:193], v[138:141], v[18:33]
	ds_read_b128 v[156:159], v198 offset:4608
	s_waitcnt lgkmcnt(5)
	v_mfma_f32_32x32x16_bf16 v[2:17], v[194:197], v[138:141], v[2:17]
	ds_read_b128 v[186:189], v198 offset:4640
	s_waitcnt lgkmcnt(5)
	v_mfma_f32_32x32x16_bf16 v[66:81], v[82:85], v[98:101], 0
	ds_read_b128 v[190:193], v198 offset:4672
	s_waitcnt lgkmcnt(5)
	v_mfma_f32_32x32x16_bf16 v[66:81], v[86:89], v[102:105], v[66:81]
	ds_read_b128 v[194:197], v198 offset:4704
	s_waitcnt lgkmcnt(5)
	v_mfma_f32_32x32x16_bf16 v[66:81], v[90:93], v[106:109], v[66:81]
	s_waitcnt lgkmcnt(4)
	v_mfma_f32_32x32x16_bf16 v[66:81], v[94:97], v[110:113], v[66:81]
	s_waitcnt lgkmcnt(3)
	v_mfma_f32_32x32x16_bf16 v[82:97], v[156:159], v[98:101], 0
	s_waitcnt lgkmcnt(2)
	v_mfma_f32_32x32x16_bf16 v[82:97], v[186:189], v[102:105], v[82:97]
	s_waitcnt lgkmcnt(1)
	v_mfma_f32_32x32x16_bf16 v[82:97], v[190:193], v[106:109], v[82:97]
	s_waitcnt lgkmcnt(0)
	v_mfma_f32_32x32x16_bf16 v[82:97], v[194:197], v[110:113], v[82:97]
	s_branch .LBB0_335

; #define LAS __attribute__((address_space(3)))
; __device__ __forceinline__ unsigned pk2(float lo, float hi) { v2f v = {lo, hi}; return __builtin_bit_cast(unsigned, __builtin_convertvector(v, v2bf)); }
; __device__ __forceinline__ void d2_softmax(v16f& S, const float c1, const LAS float* tp, float& m, float& l, v16f (&O)[4], v8s (&P)[2]) {
;     float tmax = NEGBIG;
; #pragma unroll
;     for (int i = 0; i < 16; ++i) { S[i] = S[i] * c1 + tp[(i & 3) + 8 * (i >> 2)]; tmax = fmaxf(tmax, S[i]); }
;     tmax = fmaxf(tmax, __shfl_xor(tmax, 32));
;     const float mo = m;
;     if (__any(tmax > mo + 8.f)) {
;         const float mn = (tmax > mo + 8.f) ? tmax : mo;
;         const float alpha = __builtin_amdgcn_exp2f(mo - mn);
;         l *= alpha;
; #pragma unroll
;         for (int eb = 0; eb < 4; ++eb)
; #pragma unroll
;             for (int i = 0; i < 16; ++i) O[eb][i] *= alpha;
;         m = mn;
;     }
;     const float mc = m;
;     float ps = 0.f;
; #pragma unroll
;     for (int i = 0; i < 16; ++i) { S[i] = __builtin_amdgcn_exp2f(S[i] - mc); ps += S[i]; }
;     l += ps;
; #pragma unroll
;     for (int s2 = 0; s2 < 2; ++s2) { v4u w; w.x = pk2(S[8 * s2 + 0], S[8 * s2 + 1]); w.y = pk2(S[8 * s2 + 2], S[8 * s2 + 3]); w.z = pk2(S[8 * s2 + 4], S[8 * s2 + 5]); w.w = pk2(S[8 * s2 + 6], S[8 * s2 + 7]);
;         P[s2] = __builtin_bit_cast(v8s, w); }
; }
.LBB0_335:
	s_andn2_saveexec_b64 s[18:19], s[10:11]
	s_cbranch_execz .LBB0_341
	v_med3_i32 v0, v183, s16, v214
	v_add_u32_e32 v156, 32, v183
	v_lshl_add_u32 v0, v0, 2, s23
	v_med3_i32 v156, v156, s16, v214
	v_add_u32_e32 v0, 0xa80, v0
	v_lshl_add_u32 v156, v156, 2, s23
	ds_read2_b32 v[134:135], v0 offset1:1
	ds_read2_b32 v[130:131], v0 offset0:2 offset1:3
	ds_read2_b32 v[132:133], v0 offset0:8 offset1:9
	ds_read2_b32 v[136:137], v0 offset0:10 offset1:11
	ds_read2_b32 v[138:139], v0 offset0:16 offset1:17
	ds_read2_b32 v[140:141], v0 offset0:18 offset1:19
	ds_read2_b32 v[142:143], v0 offset0:24 offset1:25
	ds_read2_b32 v[144:145], v0 offset0:26 offset1:27
	v_add_u32_e32 v156, 0xa80, v156
	ds_read2_b32 v[186:187], v156 offset1:1
	ds_read2_b32 v[188:189], v156 offset0:2 offset1:3
	ds_read2_b32 v[190:191], v156 offset0:8 offset1:9
	ds_read2_b32 v[192:193], v156 offset0:10 offset1:11
	ds_read2_b32 v[194:195], v156 offset0:16 offset1:17
	ds_read2_b32 v[196:197], v156 offset0:18 offset1:19
	ds_read2_b32 v[198:199], v156 offset0:24 offset1:25
	s_waitcnt lgkmcnt(14)
	v_fmac_f32_e32 v135, 0x3e38aa3b, v67
	v_fmamk_f32 v0, v66, 0x3e38aa3b, v134
	ds_read2_b32 v[200:201], v156 offset0:26 offset1:27
	v_max3_f32 v66, v0, s15, v135
	s_waitcnt lgkmcnt(14)
	v_fmamk_f32 v68, v68, 0x3e38aa3b, v130
	v_fmac_f32_e32 v131, 0x3e38aa3b, v69
	v_max3_f32 v66, v66, v68, v131
	s_waitcnt lgkmcnt(13)
	v_fmamk_f32 v70, v70, 0x3e38aa3b, v132
	v_fmac_f32_e32 v133, 0x3e38aa3b, v71
	v_max3_f32 v66, v66, v70, v133
	s_waitcnt lgkmcnt(12)
	v_fmamk_f32 v72, v72, 0x3e38aa3b, v136
	v_fmac_f32_e32 v137, 0x3e38aa3b, v73
	v_max3_f32 v66, v66, v72, v137
	s_waitcnt lgkmcnt(11)
	v_fmamk_f32 v74, v74, 0x3e38aa3b, v138
	v_fmac_f32_e32 v139, 0x3e38aa3b, v75
	v_max3_f32 v66, v66, v74, v139
	s_waitcnt lgkmcnt(10)
	v_fmamk_f32 v76, v76, 0x3e38aa3b, v140
	v_fmac_f32_e32 v141, 0x3e38aa3b, v77
	v_max3_f32 v66, v66, v76, v141
	s_waitcnt lgkmcnt(9)
	v_fmamk_f32 v78, v78, 0x3e38aa3b, v142
	v_fmac_f32_e32 v143, 0x3e38aa3b, v79
	v_max3_f32 v66, v66, v78, v143
	s_waitcnt lgkmcnt(8)
	v_fmamk_f32 v80, v80, 0x3e38aa3b, v144
	v_fmac_f32_e32 v145, 0x3e38aa3b, v81
	v_max3_f32 v66, v66, v80, v145
	v_add_f32_e32 v130, 0x41000000, v184
	v_mov_b32_e32 v67, v66
	s_nop 1
	v_permlane32_swap_b32_e32 v67, v66
	v_max_f32_e32 v66, v66, v67
	v_cmp_gt_f32_e32 vcc, v66, v130
	s_cbranch_vccz .Ld2x0_a
	s_nop 0
	v_cndmask_b32_e32 v67, v184, v66, vcc
	v_sub_f32_e32 v66, v184, v67
	v_exp_f32_e32 v66, v66
	v_add_f32_e32 v130, 0x41000000, v67
	v_mov_b32_e32 v184, v67
	v_mul_f32_e32 v154, v154, v66
	v_pk_mul_f32 v[64:65], v[64:65], v[66:67] op_sel_hi:[1,0]
	v_pk_mul_f32 v[62:63], v[62:63], v[66:67] op_sel_hi:[1,0]
	v_pk_mul_f32 v[60:61], v[60:61], v[66:67] op_sel_hi:[1,0]
	v_pk_mul_f32 v[58:59], v[58:59], v[66:67] op_sel_hi:[1,0]
	v_pk_mul_f32 v[56:57], v[56:57], v[66:67] op_sel_hi:[1,0]
	v_pk_mul_f32 v[54:55], v[54:55], v[66:67] op_sel_hi:[1,0]
	v_pk_mul_f32 v[52:53], v[52:53], v[66:67] op_sel_hi:[1,0]
	v_pk_mul_f32 v[50:51], v[50:51], v[66:67] op_sel_hi:[1,0]
	v_pk_mul_f32 v[48:49], v[48:49], v[66:67] op_sel_hi:[1,0]
	v_pk_mul_f32 v[46:47], v[46:47], v[66:67] op_sel_hi:[1,0]
	v_pk_mul_f32 v[44:45], v[44:45], v[66:67] op_sel_hi:[1,0]
	v_pk_mul_f32 v[42:43], v[42:43], v[66:67] op_sel_hi:[1,0]
	v_pk_mul_f32 v[40:41], v[40:41], v[66:67] op_sel_hi:[1,0]
	v_pk_mul_f32 v[38:39], v[38:39], v[66:67] op_sel_hi:[1,0]
	v_pk_mul_f32 v[36:37], v[36:37], v[66:67] op_sel_hi:[1,0]
	v_pk_mul_f32 v[34:35], v[34:35], v[66:67] op_sel_hi:[1,0]
	v_pk_mul_f32 v[32:33], v[32:33], v[66:67] op_sel_hi:[1,0]
	v_pk_mul_f32 v[30:31], v[30:31], v[66:67] op_sel_hi:[1,0]
	v_pk_mul_f32 v[28:29], v[28:29], v[66:67] op_sel_hi:[1,0]
	v_pk_mul_f32 v[26:27], v[26:27], v[66:67] op_sel_hi:[1,0]
	v_pk_mul_f32 v[24:25], v[24:25], v[66:67] op_sel_hi:[1,0]
	v_pk_mul_f32 v[22:23], v[22:23], v[66:67] op_sel_hi:[1,0]
	v_pk_mul_f32 v[20:21], v[20:21], v[66:67] op_sel_hi:[1,0]
	v_pk_mul_f32 v[18:19], v[18:19], v[66:67] op_sel_hi:[1,0]
	v_pk_mul_f32 v[16:17], v[16:17], v[66:67] op_sel_hi:[1,0]
	v_pk_mul_f32 v[14:15], v[14:15], v[66:67] op_sel_hi:[1,0]
	v_pk_mul_f32 v[12:13], v[12:13], v[66:67] op_sel_hi:[1,0]
	v_pk_mul_f32 v[10:11], v[10:11], v[66:67] op_sel_hi:[1,0]
	v_pk_mul_f32 v[8:9], v[8:9], v[66:67] op_sel_hi:[1,0]
	v_pk_mul_f32 v[6:7], v[6:7], v[66:67] op_sel_hi:[1,0]
	v_pk_mul_f32 v[4:5], v[4:5], v[66:67] op_sel_hi:[1,0]
	v_pk_mul_f32 v[2:3], v[2:3], v[66:67] op_sel_hi:[1,0]
; #define LAS __attribute__((address_space(3)))
; __device__ __forceinline__ unsigned pk2(float lo, float hi) { v2f v = {lo, hi}; return __builtin_bit_cast(unsigned, __builtin_convertvector(v, v2bf)); }
; __device__ __forceinline__ void d2_softmax(v16f& S, const float c1, const LAS float* tp, float& m, float& l, v16f (&O)[4], v8s (&P)[2]) {
;     float tmax = NEGBIG;
; #pragma unroll
;     for (int i = 0; i < 16; ++i) { S[i] = S[i] * c1 + tp[(i & 3) + 8 * (i >> 2)]; tmax = fmaxf(tmax, S[i]); }
;     tmax = fmaxf(tmax, __shfl_xor(tmax, 32));
;     const float mo = m;
;     if (__any(tmax > mo + 8.f)) {
;         const float mn = (tmax > mo + 8.f) ? tmax : mo;
;         const float alpha = __builtin_amdgcn_exp2f(mo - mn);
;         l *= alpha;
; #pragma unroll
;         for (int eb = 0; eb < 4; ++eb)
; #pragma unroll
;             for (int i = 0; i < 16; ++i) O[eb][i] *= alpha;
;         m = mn;
;     }
;     const float mc = m;
;     float ps = 0.f;
; #pragma unroll
;     for (int i = 0; i < 16; ++i) { S[i] = __builtin_amdgcn_exp2f(S[i] - mc); ps += S[i]; }
;     l += ps;
; #pragma unroll
;     for (int s2 = 0; s2 < 2; ++s2) { v4u w; w.x = pk2(S[8 * s2 + 0], S[8 * s2 + 1]); w.y = pk2(S[8 * s2 + 2], S[8 * s2 + 3]); w.z = pk2(S[8 * s2 + 4], S[8 * s2 + 5]); w.w = pk2(S[8 * s2 + 6], S[8 * s2 + 7]);
;         P[s2] = __builtin_bit_cast(v8s, w); }
; }
.Ld2x0_a:
	v_sub_f32_e32 v66, v0, v184
	v_exp_f32_e32 v66, v66
	v_sub_f32_e32 v67, v135, v184
	v_exp_f32_e32 v67, v67
	v_sub_f32_e32 v68, v68, v184
	v_exp_f32_e32 v68, v68
	v_sub_f32_e32 v69, v131, v184
	v_exp_f32_e32 v69, v69
	v_sub_f32_e32 v70, v70, v184
	v_add_f32_e32 v0, 0, v66
	v_exp_f32_e32 v70, v70
	v_sub_f32_e32 v71, v133, v184
	v_add_f32_e32 v0, v67, v0
	v_exp_f32_e32 v71, v71
	v_sub_f32_e32 v72, v72, v184
	v_add_f32_e32 v0, v68, v0
	v_exp_f32_e32 v72, v72
	v_sub_f32_e32 v73, v137, v184
	v_add_f32_e32 v0, v69, v0
	v_exp_f32_e32 v73, v73
	v_sub_f32_e32 v74, v74, v184
	v_add_f32_e32 v0, v70, v0
	v_exp_f32_e32 v74, v74
	v_sub_f32_e32 v75, v139, v184
	v_add_f32_e32 v0, v71, v0
	v_exp_f32_e32 v75, v75
	v_sub_f32_e32 v76, v76, v184
	v_add_f32_e32 v0, v72, v0
	v_exp_f32_e32 v76, v76
	v_sub_f32_e32 v77, v141, v184
	v_add_f32_e32 v0, v73, v0
	v_exp_f32_e32 v77, v77
	v_sub_f32_e32 v78, v78, v184
	v_add_f32_e32 v0, v74, v0
	v_exp_f32_e32 v78, v78
	v_sub_f32_e32 v79, v143, v184
	v_add_f32_e32 v0, v75, v0
	v_exp_f32_e32 v79, v79
	v_sub_f32_e32 v80, v80, v184
	v_add_f32_e32 v0, v76, v0
	v_exp_f32_e32 v80, v80
	v_sub_f32_e32 v81, v145, v184
	v_add_f32_e32 v0, v77, v0
	v_exp_f32_e32 v81, v81
	v_add_f32_e32 v0, v78, v0
	v_add_f32_e32 v0, v79, v0
	v_add_f32_e32 v0, v80, v0
	v_add_f32_e32 v0, v81, v0
	v_add_f32_e32 v0, v154, v0
	s_waitcnt lgkmcnt(7)
	v_fmamk_f32 v82, v82, 0x3e38aa3b, v186
	v_fmac_f32_e32 v187, 0x3e38aa3b, v83
	v_max3_f32 v83, v82, s15, v187
	s_waitcnt lgkmcnt(6)
	v_fmamk_f32 v84, v84, 0x3e38aa3b, v188
	v_fmac_f32_e32 v189, 0x3e38aa3b, v85
	v_max3_f32 v83, v83, v84, v189
	s_waitcnt lgkmcnt(5)
	v_fmamk_f32 v86, v86, 0x3e38aa3b, v190
	v_fmac_f32_e32 v191, 0x3e38aa3b, v87
	v_max3_f32 v83, v83, v86, v191
	s_waitcnt lgkmcnt(4)
	v_fmamk_f32 v88, v88, 0x3e38aa3b, v192
	v_fmac_f32_e32 v193, 0x3e38aa3b, v89
	v_max3_f32 v83, v83, v88, v193
	s_waitcnt lgkmcnt(3)
	v_fmamk_f32 v90, v90, 0x3e38aa3b, v194
	v_fmac_f32_e32 v195, 0x3e38aa3b, v91
	v_max3_f32 v83, v83, v90, v195
	s_waitcnt lgkmcnt(2)
	v_fmamk_f32 v92, v92, 0x3e38aa3b, v196
	v_fmac_f32_e32 v197, 0x3e38aa3b, v93
	v_max3_f32 v83, v83, v92, v197
	s_waitcnt lgkmcnt(1)
	v_fmamk_f32 v94, v94, 0x3e38aa3b, v198
	v_fmac_f32_e32 v199, 0x3e38aa3b, v95
	v_max3_f32 v83, v83, v94, v199
	s_waitcnt lgkmcnt(0)
	v_fmamk_f32 v96, v96, 0x3e38aa3b, v200
	v_fmac_f32_e32 v201, 0x3e38aa3b, v97
	v_max3_f32 v83, v83, v96, v201
	v_mov_b32_e32 v85, v83
	s_nop 1
	v_permlane32_swap_b32_e32 v85, v83
	v_max_f32_e32 v83, v83, v85
	v_cmp_gt_f32_e32 vcc, v83, v130
	s_cbranch_vccz .Ld2x0_b
	s_nop 0
	v_cndmask_b32_e32 v83, v184, v83, vcc
	v_sub_f32_e32 v85, v184, v83
	v_exp_f32_e32 v130, v85
	v_mov_b32_e32 v184, v83
	v_mul_f32_e32 v0, v0, v130
	v_pk_mul_f32 v[64:65], v[64:65], v[130:131] op_sel_hi:[1,0]
	v_pk_mul_f32 v[62:63], v[62:63], v[130:131] op_sel_hi:[1,0]
	v_pk_mul_f32 v[60:61], v[60:61], v[130:131] op_sel_hi:[1,0]
	v_pk_mul_f32 v[58:59], v[58:59], v[130:131] op_sel_hi:[1,0]
	v_pk_mul_f32 v[56:57], v[56:57], v[130:131] op_sel_hi:[1,0]
	v_pk_mul_f32 v[54:55], v[54:55], v[130:131] op_sel_hi:[1,0]
	v_pk_mul_f32 v[52:53], v[52:53], v[130:131] op_sel_hi:[1,0]
	v_pk_mul_f32 v[50:51], v[50:51], v[130:131] op_sel_hi:[1,0]
	v_pk_mul_f32 v[48:49], v[48:49], v[130:131] op_sel_hi:[1,0]
	v_pk_mul_f32 v[46:47], v[46:47], v[130:131] op_sel_hi:[1,0]
	v_pk_mul_f32 v[44:45], v[44:45], v[130:131] op_sel_hi:[1,0]
	v_pk_mul_f32 v[42:43], v[42:43], v[130:131] op_sel_hi:[1,0]
	v_pk_mul_f32 v[40:41], v[40:41], v[130:131] op_sel_hi:[1,0]
	v_pk_mul_f32 v[38:39], v[38:39], v[130:131] op_sel_hi:[1,0]
	v_pk_mul_f32 v[36:37], v[36:37], v[130:131] op_sel_hi:[1,0]
	v_pk_mul_f32 v[34:35], v[34:35], v[130:131] op_sel_hi:[1,0]
	v_pk_mul_f32 v[32:33], v[32:33], v[130:131] op_sel_hi:[1,0]
	v_pk_mul_f32 v[30:31], v[30:31], v[130:131] op_sel_hi:[1,0]
	v_pk_mul_f32 v[28:29], v[28:29], v[130:131] op_sel_hi:[1,0]
	v_pk_mul_f32 v[26:27], v[26:27], v[130:131] op_sel_hi:[1,0]
	v_pk_mul_f32 v[24:25], v[24:25], v[130:131] op_sel_hi:[1,0]
	v_pk_mul_f32 v[22:23], v[22:23], v[130:131] op_sel_hi:[1,0]
	v_pk_mul_f32 v[20:21], v[20:21], v[130:131] op_sel_hi:[1,0]
	v_pk_mul_f32 v[18:19], v[18:19], v[130:131] op_sel_hi:[1,0]
	v_pk_mul_f32 v[16:17], v[16:17], v[130:131] op_sel_hi:[1,0]
	v_pk_mul_f32 v[14:15], v[14:15], v[130:131] op_sel_hi:[1,0]
	v_pk_mul_f32 v[12:13], v[12:13], v[130:131] op_sel_hi:[1,0]
	v_pk_mul_f32 v[10:11], v[10:11], v[130:131] op_sel_hi:[1,0]
	v_pk_mul_f32 v[8:9], v[8:9], v[130:131] op_sel_hi:[1,0]
	v_pk_mul_f32 v[6:7], v[6:7], v[130:131] op_sel_hi:[1,0]
	v_pk_mul_f32 v[4:5], v[4:5], v[130:131] op_sel_hi:[1,0]
	v_pk_mul_f32 v[2:3], v[2:3], v[130:131] op_sel_hi:[1,0]
; #define LAS __attribute__((address_space(3)))
; __device__ __forceinline__ unsigned pk2(float lo, float hi) { v2f v = {lo, hi}; return __builtin_bit_cast(unsigned, __builtin_convertvector(v, v2bf)); }
; __device__ __forceinline__ void d2_softmax(v16f& S, const float c1, const LAS float* tp, float& m, float& l, v16f (&O)[4], v8s (&P)[2]) {
;     float tmax = NEGBIG;
; #pragma unroll
;     for (int i = 0; i < 16; ++i) { S[i] = S[i] * c1 + tp[(i & 3) + 8 * (i >> 2)]; tmax = fmaxf(tmax, S[i]); }
;     tmax = fmaxf(tmax, __shfl_xor(tmax, 32));
;     const float mo = m;
;     if (__any(tmax > mo + 8.f)) {
;         const float mn = (tmax > mo + 8.f) ? tmax : mo;
;         const float alpha = __builtin_amdgcn_exp2f(mo - mn);
;         l *= alpha;
; #pragma unroll
;         for (int eb = 0; eb < 4; ++eb)
; #pragma unroll
;             for (int i = 0; i < 16; ++i) O[eb][i] *= alpha;
;         m = mn;
;     }
;     const float mc = m;
;     float ps = 0.f;
; #pragma unroll
;     for (int i = 0; i < 16; ++i) { S[i] = __builtin_amdgcn_exp2f(S[i] - mc); ps += S[i]; }
;     l += ps;
; #pragma unroll
;     for (int s2 = 0; s2 < 2; ++s2) { v4u w; w.x = pk2(S[8 * s2 + 0], S[8 * s2 + 1]); w.y = pk2(S[8 * s2 + 2], S[8 * s2 + 3]); w.z = pk2(S[8 * s2 + 4], S[8 * s2 + 5]); w.w = pk2(S[8 * s2 + 6], S[8 * s2 + 7]);
;         P[s2] = __builtin_bit_cast(v8s, w); }
; }
.Ld2x0_b:
	v_sub_f32_e32 v82, v82, v184
	v_exp_f32_e32 v82, v82
	v_sub_f32_e32 v83, v187, v184
	v_exp_f32_e32 v83, v83
	v_sub_f32_e32 v84, v84, v184
	v_exp_f32_e32 v84, v84
	v_sub_f32_e32 v85, v189, v184
	v_exp_f32_e32 v85, v85
	v_sub_f32_e32 v86, v86, v184
	v_add_f32_e32 v156, 0, v82
	v_exp_f32_e32 v86, v86
	v_sub_f32_e32 v87, v191, v184
	v_add_f32_e32 v156, v83, v156
	v_exp_f32_e32 v87, v87
	v_sub_f32_e32 v88, v88, v184
	v_add_f32_e32 v156, v84, v156
	v_exp_f32_e32 v88, v88
	v_sub_f32_e32 v89, v193, v184
	v_add_f32_e32 v156, v85, v156
	v_exp_f32_e32 v89, v89
	v_sub_f32_e32 v90, v90, v184
	v_add_f32_e32 v156, v86, v156
	v_exp_f32_e32 v90, v90
	v_sub_f32_e32 v91, v195, v184
	v_add_f32_e32 v156, v87, v156
	v_exp_f32_e32 v91, v91
	v_sub_f32_e32 v92, v92, v184
	v_add_f32_e32 v156, v88, v156
	v_exp_f32_e32 v92, v92
	v_sub_f32_e32 v93, v197, v184
	v_add_f32_e32 v156, v89, v156
	v_exp_f32_e32 v93, v93
	v_sub_f32_e32 v94, v94, v184
	v_add_f32_e32 v156, v90, v156
	v_exp_f32_e32 v94, v94
	v_sub_f32_e32 v95, v199, v184
	v_add_f32_e32 v156, v91, v156
	v_exp_f32_e32 v95, v95
	v_sub_f32_e32 v96, v96, v184
	v_add_f32_e32 v156, v92, v156
	v_exp_f32_e32 v96, v96
	v_sub_f32_e32 v97, v201, v184
	v_add_f32_e32 v156, v93, v156
	v_exp_f32_e32 v97, v97
	v_cvt_pk_bf16_f32 v134, v66, v67
	v_add_f32_e32 v156, v94, v156
	v_cvt_pk_bf16_f32 v135, v68, v69
	v_add_f32_e32 v156, v95, v156
	v_cvt_pk_bf16_f32 v136, v70, v71
	v_add_f32_e32 v156, v96, v156
	v_cvt_pk_bf16_f32 v137, v72, v73
	v_add_f32_e32 v156, v97, v156
	v_cvt_pk_bf16_f32 v130, v74, v75
	v_cvt_pk_bf16_f32 v131, v76, v77
	v_cvt_pk_bf16_f32 v132, v78, v79
	v_cvt_pk_bf16_f32 v133, v80, v81
	v_add_f32_e32 v154, v0, v156
	v_cvt_pk_bf16_f32 v142, v82, v83
	v_cvt_pk_bf16_f32 v143, v84, v85
	v_cvt_pk_bf16_f32 v144, v86, v87
	v_cvt_pk_bf16_f32 v145, v88, v89
	v_cvt_pk_bf16_f32 v138, v90, v91
	v_cvt_pk_bf16_f32 v139, v92, v93
	v_cvt_pk_bf16_f32 v140, v94, v95
	v_cvt_pk_bf16_f32 v141, v96, v97
.LBB0_341:
	s_or_b64 exec, exec, s[18:19]
	s_waitcnt lgkmcnt(0)
	s_barrier
	s_and_saveexec_b64 s[10:11], s[38:39]
	s_xor_b64 s[18:19], exec, s[10:11]
	s_cbranch_execz .LBB0_347
	v_med3_i32 v0, v183, s16, v214
	v_add_u32_e32 v156, 32, v183
	v_lshl_add_u32 v0, v0, 2, s23
	v_med3_i32 v156, v156, s16, v214
	v_add_u32_e32 v0, 0xa80, v0
	v_lshl_add_u32 v156, v156, 2, s23
	ds_read2_b32 v[134:135], v0 offset1:1
	ds_read2_b32 v[130:131], v0 offset0:2 offset1:3
	ds_read2_b32 v[132:133], v0 offset0:8 offset1:9
	ds_read2_b32 v[136:137], v0 offset0:10 offset1:11
	ds_read2_b32 v[138:139], v0 offset0:16 offset1:17
	ds_read2_b32 v[140:141], v0 offset0:18 offset1:19
	ds_read2_b32 v[142:143], v0 offset0:24 offset1:25
	ds_read2_b32 v[144:145], v0 offset0:26 offset1:27
	v_add_u32_e32 v156, 0xa80, v156
	ds_read2_b32 v[186:187], v156 offset1:1
	ds_read2_b32 v[188:189], v156 offset0:2 offset1:3
	ds_read2_b32 v[190:191], v156 offset0:8 offset1:9
	ds_read2_b32 v[192:193], v156 offset0:10 offset1:11
	ds_read2_b32 v[194:195], v156 offset0:16 offset1:17
	ds_read2_b32 v[196:197], v156 offset0:18 offset1:19
	ds_read2_b32 v[198:199], v156 offset0:24 offset1:25
	s_waitcnt lgkmcnt(14)
	v_fmac_f32_e32 v135, 0x3e38aa3b, v67
	v_fmamk_f32 v0, v66, 0x3e38aa3b, v134
	ds_read2_b32 v[200:201], v156 offset0:26 offset1:27
	v_max3_f32 v66, v0, s15, v135
	s_waitcnt lgkmcnt(14)
	v_fmamk_f32 v68, v68, 0x3e38aa3b, v130
	v_fmac_f32_e32 v131, 0x3e38aa3b, v69
	v_max3_f32 v66, v66, v68, v131
	s_waitcnt lgkmcnt(13)
	v_fmamk_f32 v70, v70, 0x3e38aa3b, v132
	v_fmac_f32_e32 v133, 0x3e38aa3b, v71
	v_max3_f32 v66, v66, v70, v133
	s_waitcnt lgkmcnt(12)
	v_fmamk_f32 v72, v72, 0x3e38aa3b, v136
	v_fmac_f32_e32 v137, 0x3e38aa3b, v73
	v_max3_f32 v66, v66, v72, v137
	s_waitcnt lgkmcnt(11)
	v_fmamk_f32 v74, v74, 0x3e38aa3b, v138
	v_fmac_f32_e32 v139, 0x3e38aa3b, v75
	v_max3_f32 v66, v66, v74, v139
	s_waitcnt lgkmcnt(10)
	v_fmamk_f32 v76, v76, 0x3e38aa3b, v140
	v_fmac_f32_e32 v141, 0x3e38aa3b, v77
	v_max3_f32 v66, v66, v76, v141
	s_waitcnt lgkmcnt(9)
	v_fmamk_f32 v78, v78, 0x3e38aa3b, v142
	v_fmac_f32_e32 v143, 0x3e38aa3b, v79
	v_max3_f32 v66, v66, v78, v143
	s_waitcnt lgkmcnt(8)
	v_fmamk_f32 v80, v80, 0x3e38aa3b, v144
	v_fmac_f32_e32 v145, 0x3e38aa3b, v81
	v_max3_f32 v66, v66, v80, v145
	v_add_f32_e32 v130, 0x41000000, v184
	v_mov_b32_e32 v67, v66
	s_nop 1
	v_permlane32_swap_b32_e32 v67, v66
	v_max_f32_e32 v66, v66, v67
	v_cmp_gt_f32_e32 vcc, v66, v130
	s_cbranch_vccz .Ld2x1_a
	s_nop 0
	v_cndmask_b32_e32 v67, v184, v66, vcc
	v_sub_f32_e32 v66, v184, v67
	v_exp_f32_e32 v66, v66
	v_add_f32_e32 v130, 0x41000000, v67
	v_mov_b32_e32 v184, v67
	v_mul_f32_e32 v154, v154, v66
	v_pk_mul_f32 v[64:65], v[64:65], v[66:67] op_sel_hi:[1,0]
	v_pk_mul_f32 v[62:63], v[62:63], v[66:67] op_sel_hi:[1,0]
	v_pk_mul_f32 v[60:61], v[60:61], v[66:67] op_sel_hi:[1,0]
	v_pk_mul_f32 v[58:59], v[58:59], v[66:67] op_sel_hi:[1,0]
	v_pk_mul_f32 v[56:57], v[56:57], v[66:67] op_sel_hi:[1,0]
	v_pk_mul_f32 v[54:55], v[54:55], v[66:67] op_sel_hi:[1,0]
	v_pk_mul_f32 v[52:53], v[52:53], v[66:67] op_sel_hi:[1,0]
	v_pk_mul_f32 v[50:51], v[50:51], v[66:67] op_sel_hi:[1,0]
	v_pk_mul_f32 v[48:49], v[48:49], v[66:67] op_sel_hi:[1,0]
	v_pk_mul_f32 v[46:47], v[46:47], v[66:67] op_sel_hi:[1,0]
	v_pk_mul_f32 v[44:45], v[44:45], v[66:67] op_sel_hi:[1,0]
	v_pk_mul_f32 v[42:43], v[42:43], v[66:67] op_sel_hi:[1,0]
	v_pk_mul_f32 v[40:41], v[40:41], v[66:67] op_sel_hi:[1,0]
	v_pk_mul_f32 v[38:39], v[38:39], v[66:67] op_sel_hi:[1,0]
	v_pk_mul_f32 v[36:37], v[36:37], v[66:67] op_sel_hi:[1,0]
	v_pk_mul_f32 v[34:35], v[34:35], v[66:67] op_sel_hi:[1,0]
	v_pk_mul_f32 v[32:33], v[32:33], v[66:67] op_sel_hi:[1,0]
	v_pk_mul_f32 v[30:31], v[30:31], v[66:67] op_sel_hi:[1,0]
	v_pk_mul_f32 v[28:29], v[28:29], v[66:67] op_sel_hi:[1,0]
	v_pk_mul_f32 v[26:27], v[26:27], v[66:67] op_sel_hi:[1,0]
	v_pk_mul_f32 v[24:25], v[24:25], v[66:67] op_sel_hi:[1,0]
	v_pk_mul_f32 v[22:23], v[22:23], v[66:67] op_sel_hi:[1,0]
	v_pk_mul_f32 v[20:21], v[20:21], v[66:67] op_sel_hi:[1,0]
	v_pk_mul_f32 v[18:19], v[18:19], v[66:67] op_sel_hi:[1,0]
	v_pk_mul_f32 v[16:17], v[16:17], v[66:67] op_sel_hi:[1,0]
	v_pk_mul_f32 v[14:15], v[14:15], v[66:67] op_sel_hi:[1,0]
	v_pk_mul_f32 v[12:13], v[12:13], v[66:67] op_sel_hi:[1,0]
	v_pk_mul_f32 v[10:11], v[10:11], v[66:67] op_sel_hi:[1,0]
	v_pk_mul_f32 v[8:9], v[8:9], v[66:67] op_sel_hi:[1,0]
	v_pk_mul_f32 v[6:7], v[6:7], v[66:67] op_sel_hi:[1,0]
	v_pk_mul_f32 v[4:5], v[4:5], v[66:67] op_sel_hi:[1,0]
	v_pk_mul_f32 v[2:3], v[2:3], v[66:67] op_sel_hi:[1,0]

; __device__ __forceinline__ void d2_qk(const LAS unsigned char* Kb, const v8s (&Q)[4], v16f& S) {
;     const v16f z = {0.f, 0.f, 0.f, 0.f, 0.f, 0.f, 0.f, 0.f, 0.f, 0.f, 0.f, 0.f, 0.f, 0.f, 0.f, 0.f};
;     const v8s k0 = *(const LAS v8s*)Kb, k1 = *(const LAS v8s*)(Kb + 32), k2 = *(const LAS v8s*)(Kb + 64), k3 = *(const LAS v8s*)(Kb + 96);
;     __builtin_amdgcn_sched_barrier(0);
;     S = MFMA32(k0, Q[0], z); S = MFMA32(k1, Q[1], S); S = MFMA32(k2, Q[2], S); S = MFMA32(k3, Q[3], S);
;     __builtin_amdgcn_sched_barrier(0);
; }
; __device__ __forceinline__ void d2_softmax(v16f& S, const float c1, const LAS float* tp, float& m, float& l, v16f (&O)[4], v8s (&P)[2]) {
;     float tmax = NEGBIG;
; #pragma unroll
;     for (int i = 0; i < 16; ++i) { S[i] = S[i] * c1 + tp[(i & 3) + 8 * (i >> 2)]; tmax = fmaxf(tmax, S[i]); }
;     tmax = fmaxf(tmax, __shfl_xor(tmax, 32));
;     const float mo = m;
;     if (__any(tmax > mo + 8.f)) {
;         const float mn = (tmax > mo + 8.f) ? tmax : mo;
;         const float alpha = __builtin_amdgcn_exp2f(mo - mn);
;         l *= alpha;
; #pragma unroll
;         for (int eb = 0; eb < 4; ++eb)
; #pragma unroll
;             for (int i = 0; i < 16; ++i) O[eb][i] *= alpha;
;         m = mn;
;     }
;     const float mc = m;
;     float ps = 0.f;
; #pragma unroll
;     for (int i = 0; i < 16; ++i) { S[i] = __builtin_amdgcn_exp2f(S[i] - mc); ps += S[i]; }
;     l += ps;
; #pragma unroll
;     for (int s2 = 0; s2 < 2; ++s2) { v4u w; w.x = pk2(S[8 * s2 + 0], S[8 * s2 + 1]); w.y = pk2(S[8 * s2 + 2], S[8 * s2 + 3]); w.z = pk2(S[8 * s2 + 4], S[8 * s2 + 5]); w.w = pk2(S[8 * s2 + 6], S[8 * s2 + 7]);
;         P[s2] = __builtin_bit_cast(v8s, w); }
; }
; __device__ __forceinline__ void d2_pv(const LAS unsigned char* vb0, const v8s (&P)[2], v16f (&O)[4]) {
;     const LAS unsigned char* va = vb0; const LAS unsigned char* vc = vb0 + 16 * 320;
;     const v4s l0 = TRR(va), h0 = TRR(va + 2560), l1 = TRR(va + 64), h1 = TRR(va + 2624), l2 = TRR(va + 128), h2 = TRR(va + 2688), l3 = TRR(va + 192), h3 = TRR(va + 2752);
;     __builtin_amdgcn_sched_barrier(0);
;     const v4s m0 = TRR(vc), n0 = TRR(vc + 2560), m1 = TRR(vc + 64), n1 = TRR(vc + 2624), m2 = TRR(vc + 128), n2 = TRR(vc + 2688), m3 = TRR(vc + 192), n3 = TRR(vc + 2752);
;     O[0] = MFMA32(__builtin_shufflevector(l0, h0, 0, 1, 2, 3, 4, 5, 6, 7), P[0], O[0]);
.LBB0_347:
	s_andn2_saveexec_b64 s[10:11], s[18:19]
	s_cbranch_execz .LBB0_351
	s_and_b64 vcc, exec, s[40:41]
	s_cbranch_vccnz .LBB0_350
	s_bitcmp1_b32 s21, 0
	s_cselect_b32 s18, 0x4800, 0
	v_add_u32_e32 v198, s18, v181
	v_add_u32_e32 v0, s28, v180
	ds_read_b64_tr_b16 v[156:157], v0 offset:36864
	ds_read_b64_tr_b16 v[158:159], v0 offset:39424
	ds_read_b64_tr_b16 v[186:187], v0 offset:36928
	ds_read_b64_tr_b16 v[188:189], v0 offset:39488
	ds_read_b64_tr_b16 v[190:191], v0 offset:36992
	ds_read_b64_tr_b16 v[192:193], v0 offset:39552
	ds_read_b64_tr_b16 v[194:195], v0 offset:37056
	ds_read_b64_tr_b16 v[196:197], v0 offset:39616
	ds_read_b64_tr_b16 v[66:67], v0 offset:41984
	ds_read_b64_tr_b16 v[68:69], v0 offset:44544
	ds_read_b64_tr_b16 v[70:71], v0 offset:42048
	ds_read_b64_tr_b16 v[72:73], v0 offset:44608
	s_waitcnt lgkmcnt(10)
	v_mfma_f32_32x32x16_bf16 v[50:65], v[156:159], v[134:137], v[50:65]
	ds_read_b64_tr_b16 v[74:75], v0 offset:42112
	ds_read_b64_tr_b16 v[76:77], v0 offset:44672
	s_waitcnt lgkmcnt(10)
	v_mfma_f32_32x32x16_bf16 v[34:49], v[186:189], v[134:137], v[34:49]
	ds_read_b64_tr_b16 v[78:79], v0 offset:42176
	ds_read_b64_tr_b16 v[80:81], v0 offset:44736
	s_waitcnt lgkmcnt(10)
	v_mfma_f32_32x32x16_bf16 v[18:33], v[190:193], v[134:137], v[18:33]
	ds_read_b64_tr_b16 v[82:83], v0 offset:47104
	ds_read_b64_tr_b16 v[84:85], v0 offset:49664
	s_waitcnt lgkmcnt(10)
	v_mfma_f32_32x32x16_bf16 v[2:17], v[194:197], v[134:137], v[2:17]
	ds_read_b64_tr_b16 v[86:87], v0 offset:47168
	ds_read_b64_tr_b16 v[88:89], v0 offset:49728
	s_waitcnt lgkmcnt(10)
	v_mfma_f32_32x32x16_bf16 v[50:65], v[66:69], v[130:133], v[50:65]
	ds_read_b64_tr_b16 v[90:91], v0 offset:47232
	ds_read_b64_tr_b16 v[92:93], v0 offset:49792
	s_waitcnt lgkmcnt(10)
	v_mfma_f32_32x32x16_bf16 v[34:49], v[70:73], v[130:133], v[34:49]
	ds_read_b64_tr_b16 v[94:95], v0 offset:47296
	ds_read_b64_tr_b16 v[96:97], v0 offset:49856
	s_waitcnt lgkmcnt(10)
	v_mfma_f32_32x32x16_bf16 v[18:33], v[74:77], v[130:133], v[18:33]
	ds_read_b64_tr_b16 v[156:157], v0 offset:52224
	ds_read_b64_tr_b16 v[158:159], v0 offset:54784
	s_waitcnt lgkmcnt(10)
	v_mfma_f32_32x32x16_bf16 v[2:17], v[78:81], v[130:133], v[2:17]
	ds_read_b64_tr_b16 v[186:187], v0 offset:52288
	ds_read_b64_tr_b16 v[188:189], v0 offset:54848
	s_waitcnt lgkmcnt(10)
	v_mfma_f32_32x32x16_bf16 v[50:65], v[82:85], v[142:145], v[50:65]
	ds_read_b64_tr_b16 v[190:191], v0 offset:52352
	ds_read_b64_tr_b16 v[192:193], v0 offset:54912
	s_waitcnt lgkmcnt(10)
	v_mfma_f32_32x32x16_bf16 v[34:49], v[86:89], v[142:145], v[34:49]
	ds_read_b64_tr_b16 v[194:195], v0 offset:52416
	ds_read_b64_tr_b16 v[196:197], v0 offset:54976
	s_waitcnt lgkmcnt(10)
	v_mfma_f32_32x32x16_bf16 v[18:33], v[90:93], v[142:145], v[18:33]
	ds_read_b128 v[82:85], v198
	s_waitcnt lgkmcnt(9)
	v_mfma_f32_32x32x16_bf16 v[2:17], v[94:97], v[142:145], v[2:17]
	ds_read_b128 v[86:89], v198 offset:32
	s_waitcnt lgkmcnt(8)
	v_mfma_f32_32x32x16_bf16 v[50:65], v[156:159], v[138:141], v[50:65]
	ds_read_b128 v[90:93], v198 offset:64
	s_waitcnt lgkmcnt(7)
	v_mfma_f32_32x32x16_bf16 v[34:49], v[186:189], v[138:141], v[34:49]
	ds_read_b128 v[94:97], v198 offset:96
	s_waitcnt lgkmcnt(6)
	v_mfma_f32_32x32x16_bf16 v[18:33], v[190:193], v[138:141], v[18:33]
	ds_read_b128 v[156:159], v198 offset:4608
	s_waitcnt lgkmcnt(5)
	v_mfma_f32_32x32x16_bf16 v[2:17], v[194:197], v[138:141], v[2:17]
	ds_read_b128 v[186:189], v198 offset:4640
	s_waitcnt lgkmcnt(5)
	v_mfma_f32_32x32x16_bf16 v[66:81], v[82:85], v[98:101], 0
	ds_read_b128 v[190:193], v198 offset:4672
	s_waitcnt lgkmcnt(5)
	v_mfma_f32_32x32x16_bf16 v[66:81], v[86:89], v[102:105], v[66:81]
	ds_read_b128 v[194:197], v198 offset:4704
	s_waitcnt lgkmcnt(5)
	v_mfma_f32_32x32x16_bf16 v[66:81], v[90:93], v[106:109], v[66:81]
	s_waitcnt lgkmcnt(4)
	v_mfma_f32_32x32x16_bf16 v[66:81], v[94:97], v[110:113], v[66:81]
	s_waitcnt lgkmcnt(3)
	v_mfma_f32_32x32x16_bf16 v[82:97], v[156:159], v[98:101], 0
	s_waitcnt lgkmcnt(2)
	v_mfma_f32_32x32x16_bf16 v[82:97], v[186:189], v[102:105], v[82:97]
	s_waitcnt lgkmcnt(1)
	v_mfma_f32_32x32x16_bf16 v[82:97], v[190:193], v[106:109], v[82:97]
	s_waitcnt lgkmcnt(0)
	v_mfma_f32_32x32x16_bf16 v[82:97], v[194:197], v[110:113], v[82:97]
	s_branch .LBB0_351
